# P1 modulation vectors of all three ms summed once before the ms loop (26 loads in flight, parked in LDS); EpiP decay logs via scalar loads
# baseline (speedup 1.0000x reference)
; __global__ void __launch_bounds__(512, 2) fwd_megakernel(Params Parg) {
;     ...
;         f32x4 wv[4], shv[4];
; #pragma unroll 1
;         for (int ms = 0; ms < 3; ++ms) {
; #pragma unroll
;             for (int j = 0; j < 4; ++j) { const int c = 4 * lane + 256 * j;
;                 f32x4 sh = *(const f32x4*)(b_mod + c), sc = *(const f32x4*)(b_mod + D + c);
; #pragma unroll
;                 for (int p = 0; p < 8; ++p) { sh += *(const f32x4*)(part + (p * 3 + ms) * (NMOD * D) + c); sc += *(const f32x4*)(part + (p * 3 + ms) * (NMOD * D) + D + c); }
;                 shv[j] = sh; wv[j] = *(const f32x4*)(IN(6) + c) * (sc + 1.0f); }
.LBB0_225:
	s_or_b64 exec, exec, s[14:15]
	s_ashr_i32 s3, s3, 6
	v_readlane_b32 s4, v254, 2
	s_load_dwordx2 s[24:25], s[8:9], 0x30
	s_add_i32 s3, s3, s4
	v_lshlrev_b32_e32 v1, 2, v2
	s_add_u32 s4, s22, 0x1000
	v_and_b32_e32 v0, 0xfc, v1
	s_addc_u32 s5, s23, 0
	s_cmpk_lt_i32 s3, 0x2000
	v_mov_b32_e32 v5, 0
	v_lshlrev_b32_e32 v4, 2, v0
	v_or_b32_e32 v6, 0x100, v0
	s_cselect_b64 s[14:15], -1, 0
	s_lshl_b32 s16, s3, 1
	s_lshl_b32 s96, s28, 4
	v_lshl_add_u64 v[32:33], s[22:23], 0, v[4:5]
	v_lshl_add_u64 v[34:35], s[4:5], 0, v[4:5]
	s_waitcnt lgkmcnt(0)
	v_lshl_add_u64 v[36:37], s[24:25], 0, v[4:5]
	v_lshlrev_b32_e32 v4, 2, v6
	v_or_b32_e32 v8, 0x200, v0
	s_cmpk_lt_i32 s3, 0x100
	v_lshl_add_u64 v[38:39], s[4:5], 0, v[4:5]
	v_lshlrev_b32_e32 v4, 2, v8
	v_or_b32_e32 v10, 0x300, v0
	s_cselect_b64 s[18:19], -1, 0
	v_lshl_add_u64 v[40:41], s[4:5], 0, v[4:5]
	v_lshlrev_b32_e32 v4, 2, v10
	s_ashr_i32 s17, s16, 31
	v_bfrev_b32_e32 v3, 0.5
	s_movk_i32 s12, 0x80
	v_lshl_add_u64 v[42:43], s[4:5], 0, v[4:5]
	s_lshl_b64 s[4:5], s[16:17], 11
	v_bitop3_b32 v88, v1, 4, v3 bitop3:0x6c
	v_bitop3_b32 v89, v1, 8, v3 bitop3:0x6c
	v_bitop3_b32 v90, v1, 16, v3 bitop3:0x6c
	v_bitop3_b32 v91, v1, 32, v3 bitop3:0x6c
	v_bitop3_b32 v92, v1, 64, v3 bitop3:0x6c
	v_bitop3_b32 v93, v1, s12, v3 bitop3:0x6c
	v_and_b32_e32 v1, 63, v2
	s_add_u32 s4, s20, s4
	v_lshlrev_b32_e32 v4, 3, v1
	s_addc_u32 s5, s21, s5
	v_lshl_add_u64 v[2:3], s[4:5], 0, v[4:5]
	s_mov_b64 s[4:5], 0x4800800
	v_lshl_add_u64 v[44:45], v[2:3], 0, s[4:5]
	s_lshl_b64 s[4:5], s[16:17], 12
	v_lshl_or_b32 v1, v1, 4, s4
	s_ashr_i32 s97, s96, 31
	v_or_b32_e32 v46, 0x1000, v1
	v_mov_b32_e32 v47, s5
	s_mov_b64 s[4:5], 0x8800e00
	s_lshl_b64 s[68:69], s[96:97], 11
	v_lshl_add_u64 v[48:49], s[6:7], 0, v[46:47]
	s_lshl_b64 s[70:71], s[96:97], 12
	v_lshl_add_u64 v[50:51], v[2:3], 0, s[4:5]
	s_mov_b32 s21, 0
	v_lshlrev_b32_e32 v94, 2, v0
	v_lshlrev_b32_e32 v95, 2, v6
	v_lshlrev_b32_e32 v96, 2, v8
	v_lshlrev_b32_e32 v97, 2, v10
	v_mov_b32_e32 v98, 0x358637bd
	s_mov_b32 s3, 0x800000
	s_mov_b64 s[22:23], 0x2000000
	s_mov_b64 s[24:25], 0x4000000
	s_mov_b32 s4, 0
	v_readfirstlane_b32 s26, v176
	s_lshr_b32 s26, s26, 6
	s_and_b32 s38, s26, 3
	s_lshr_b32 s34, s26, 2
	s_lshl_b32 s38, s38, 10
	s_lshl_b32 s34, s34, 12
	s_add_u32 s34, s34, s38
	s_mov_b32 s35, 0
	s_mov_b32 s39, 0
	v_add_u32_e32 v0, s34, v94
	v_lshl_add_u64 v[2:3], v[32:33], 0, s[34:35]
	v_lshl_add_u64 v[4:5], v[36:37], 0, s[38:39]
	global_load_dwordx4 v[8:11], v[2:3], off
	global_load_dwordx4 v[100:103], v[4:5], off
	s_mov_b64 s[6:7], s[10:11]
	global_load_dwordx4 v[104:107], v0, s[6:7]
	s_add_u32 s6, s6, 0x1b000
	s_addc_u32 s7, s7, 0
	global_load_dwordx4 v[108:111], v0, s[6:7]
	s_add_u32 s6, s6, 0x1b000
	s_addc_u32 s7, s7, 0
	global_load_dwordx4 v[112:115], v0, s[6:7]
	s_add_u32 s6, s6, 0x1b000
	s_addc_u32 s7, s7, 0
	global_load_dwordx4 v[116:119], v0, s[6:7]
	s_add_u32 s6, s6, 0x1b000
	s_addc_u32 s7, s7, 0
	global_load_dwordx4 v[120:123], v0, s[6:7]
	s_add_u32 s6, s6, 0x1b000
	s_addc_u32 s7, s7, 0
	global_load_dwordx4 v[124:127], v0, s[6:7]
	s_add_u32 s6, s6, 0x1b000
	s_addc_u32 s7, s7, 0
	global_load_dwordx4 v[128:131], v0, s[6:7]
	s_add_u32 s6, s6, 0x1b000
	s_addc_u32 s7, s7, 0
	global_load_dwordx4 v[132:135], v0, s[6:7]
	s_add_u32 s6, s6, 0xfff4c000
	s_addc_u32 s7, s7, -1
	global_load_dwordx4 v[136:139], v0, s[6:7]
	s_add_u32 s6, s6, 0x1b000
	s_addc_u32 s7, s7, 0
	global_load_dwordx4 v[140:143], v0, s[6:7]
	s_add_u32 s6, s6, 0x1b000
	s_addc_u32 s7, s7, 0
	global_load_dwordx4 v[144:147], v0, s[6:7]
	s_add_u32 s6, s6, 0x1b000
	s_addc_u32 s7, s7, 0
	global_load_dwordx4 v[148:151], v0, s[6:7]
	s_add_u32 s6, s6, 0x1b000
	s_addc_u32 s7, s7, 0
	global_load_dwordx4 v[152:155], v0, s[6:7]
	s_add_u32 s6, s6, 0x1b000
	s_addc_u32 s7, s7, 0
	global_load_dwordx4 v[156:159], v0, s[6:7]
	s_add_u32 s6, s6, 0x1b000
	s_addc_u32 s7, s7, 0
	global_load_dwordx4 v[160:163], v0, s[6:7]
	s_add_u32 s6, s6, 0x1b000
	s_addc_u32 s7, s7, 0
	global_load_dwordx4 v[164:167], v0, s[6:7]
	s_add_u32 s6, s6, 0xfff4c000
	s_addc_u32 s7, s7, -1
	global_load_dwordx4 v[178:181], v0, s[6:7]
	s_add_u32 s6, s6, 0x1b000
	s_addc_u32 s7, s7, 0
	global_load_dwordx4 v[182:185], v0, s[6:7]
	s_add_u32 s6, s6, 0x1b000
	s_addc_u32 s7, s7, 0
	global_load_dwordx4 v[186:189], v0, s[6:7]
	s_add_u32 s6, s6, 0x1b000
	s_addc_u32 s7, s7, 0
	global_load_dwordx4 v[190:193], v0, s[6:7]
	s_add_u32 s6, s6, 0x1b000
	s_addc_u32 s7, s7, 0
	global_load_dwordx4 v[194:197], v0, s[6:7]
	s_add_u32 s6, s6, 0x1b000
	s_addc_u32 s7, s7, 0
	global_load_dwordx4 v[198:201], v0, s[6:7]
	s_add_u32 s6, s6, 0x1b000
	s_addc_u32 s7, s7, 0
	global_load_dwordx4 v[202:205], v0, s[6:7]
	s_add_u32 s6, s6, 0x1b000
	s_addc_u32 s7, s7, 0
	global_load_dwordx4 v[206:209], v0, s[6:7]
	v_and_b32_e32 v6, 63, v176
	v_mul_u32_u24_e32 v6, 0x88, v6
	s_lshl_b32 s27, s26, 4
	v_add_u32_e32 v7, s27, v6
	s_waitcnt vmcnt(23)
; __global__ void __launch_bounds__(512, 2) fwd_megakernel(Params Parg) {
;     ...
;             for (int j = 0; j < 4; ++j) { const int c = 4 * lane + 256 * j;
;                 f32x4 sh = *(const f32x4*)(b_mod + c), sc = *(const f32x4*)(b_mod + D + c);
; #pragma unroll
;                 for (int p = 0; p < 8; ++p) { sh += *(const f32x4*)(part + (p * 3 + ms) * (NMOD * D) + c); sc += *(const f32x4*)(part + (p * 3 + ms) * (NMOD * D) + D + c); }
;                 shv[j] = sh; wv[j] = *(const f32x4*)(IN(6) + c) * (sc + 1.0f); }
	v_pk_add_f32 v[12:13], v[8:9], v[104:105]
	v_pk_add_f32 v[14:15], v[10:11], v[106:107]
	s_waitcnt vmcnt(22)
	v_pk_add_f32 v[12:13], v[12:13], v[108:109]
	v_pk_add_f32 v[14:15], v[14:15], v[110:111]
	s_waitcnt vmcnt(21)
	v_pk_add_f32 v[12:13], v[12:13], v[112:113]
	v_pk_add_f32 v[14:15], v[14:15], v[114:115]
	s_waitcnt vmcnt(20)
	v_pk_add_f32 v[12:13], v[12:13], v[116:117]
	v_pk_add_f32 v[14:15], v[14:15], v[118:119]
	s_waitcnt vmcnt(19)
	v_pk_add_f32 v[12:13], v[12:13], v[120:121]
	v_pk_add_f32 v[14:15], v[14:15], v[122:123]
	s_waitcnt vmcnt(18)
	v_pk_add_f32 v[12:13], v[12:13], v[124:125]
	v_pk_add_f32 v[14:15], v[14:15], v[126:127]
	s_waitcnt vmcnt(17)
	v_pk_add_f32 v[12:13], v[12:13], v[128:129]
	v_pk_add_f32 v[14:15], v[14:15], v[130:131]
	s_waitcnt vmcnt(16)
	v_pk_add_f32 v[12:13], v[12:13], v[132:133]
	v_pk_add_f32 v[14:15], v[14:15], v[134:135]
	s_waitcnt vmcnt(15)
	v_pk_add_f32 v[16:17], v[8:9], v[136:137]
	v_pk_add_f32 v[18:19], v[10:11], v[138:139]
	s_waitcnt vmcnt(14)
	v_pk_add_f32 v[16:17], v[16:17], v[140:141]
	v_pk_add_f32 v[18:19], v[18:19], v[142:143]
	s_waitcnt vmcnt(13)
	v_pk_add_f32 v[16:17], v[16:17], v[144:145]
	v_pk_add_f32 v[18:19], v[18:19], v[146:147]
	s_waitcnt vmcnt(12)
	v_pk_add_f32 v[16:17], v[16:17], v[148:149]
	v_pk_add_f32 v[18:19], v[18:19], v[150:151]
	s_waitcnt vmcnt(11)
	v_pk_add_f32 v[16:17], v[16:17], v[152:153]
	v_pk_add_f32 v[18:19], v[18:19], v[154:155]
	s_waitcnt vmcnt(10)
	v_pk_add_f32 v[16:17], v[16:17], v[156:157]
	v_pk_add_f32 v[18:19], v[18:19], v[158:159]
	s_waitcnt vmcnt(9)
	v_pk_add_f32 v[16:17], v[16:17], v[160:161]
	v_pk_add_f32 v[18:19], v[18:19], v[162:163]
	s_waitcnt vmcnt(8)
	v_pk_add_f32 v[16:17], v[16:17], v[164:165]
	v_pk_add_f32 v[18:19], v[18:19], v[166:167]
	s_waitcnt vmcnt(7)
	v_pk_add_f32 v[20:21], v[8:9], v[178:179]
	v_pk_add_f32 v[22:23], v[10:11], v[180:181]
	s_waitcnt vmcnt(6)
	v_pk_add_f32 v[20:21], v[20:21], v[182:183]
	v_pk_add_f32 v[22:23], v[22:23], v[184:185]
	s_waitcnt vmcnt(5)
	v_pk_add_f32 v[20:21], v[20:21], v[186:187]
	v_pk_add_f32 v[22:23], v[22:23], v[188:189]
	s_waitcnt vmcnt(4)
	v_pk_add_f32 v[20:21], v[20:21], v[190:191]
	v_pk_add_f32 v[22:23], v[22:23], v[192:193]
	s_waitcnt vmcnt(3)
	v_pk_add_f32 v[20:21], v[20:21], v[194:195]
	v_pk_add_f32 v[22:23], v[22:23], v[196:197]
	s_waitcnt vmcnt(2)
	v_pk_add_f32 v[20:21], v[20:21], v[198:199]
	v_pk_add_f32 v[22:23], v[22:23], v[200:201]
	s_waitcnt vmcnt(1)
	v_pk_add_f32 v[20:21], v[20:21], v[202:203]
	v_pk_add_f32 v[22:23], v[22:23], v[204:205]
	s_waitcnt vmcnt(0)
	v_pk_add_f32 v[20:21], v[20:21], v[206:207]
	v_pk_add_f32 v[22:23], v[22:23], v[208:209]
	s_cmp_lt_u32 s26, 4
	s_cbranch_scc1 .Lp1_shift_vecs
	v_pk_add_f32 v[12:13], v[12:13], 1.0 op_sel_hi:[1,0]
	v_pk_add_f32 v[14:15], v[14:15], 1.0 op_sel_hi:[1,0]
	v_pk_mul_f32 v[12:13], v[12:13], v[100:101]
	v_pk_mul_f32 v[14:15], v[14:15], v[102:103]
	v_pk_add_f32 v[16:17], v[16:17], 1.0 op_sel_hi:[1,0]
	v_pk_add_f32 v[18:19], v[18:19], 1.0 op_sel_hi:[1,0]
	v_pk_mul_f32 v[16:17], v[16:17], v[100:101]
	v_pk_mul_f32 v[18:19], v[18:19], v[102:103]
	v_pk_add_f32 v[20:21], v[20:21], 1.0 op_sel_hi:[1,0]
	v_pk_add_f32 v[22:23], v[22:23], 1.0 op_sel_hi:[1,0]
	v_pk_mul_f32 v[20:21], v[20:21], v[100:101]
	v_pk_mul_f32 v[22:23], v[22:23], v[102:103]
.Lp1_shift_vecs:
	ds_write2_b64 v7, v[12:13], v[14:15] offset1:1
	v_add_u32_e32 v7, 0x2200, v7
	ds_write2_b64 v7, v[16:17], v[18:19] offset1:1
	v_add_u32_e32 v7, 0x2200, v7
	ds_write2_b64 v7, v[20:21], v[22:23] offset1:1
	s_waitcnt lgkmcnt(0)
	s_barrier
	s_branch .LBB0_227

; __global__ void __launch_bounds__(512, 2) fwd_megakernel(Params Parg) {
;     ...
;         for (int ms = 0; ms < 3; ++ms) {
; #pragma unroll
;             for (int j = 0; j < 4; ++j) { const int c = 4 * lane + 256 * j;
;                 f32x4 sh = *(const f32x4*)(b_mod + c), sc = *(const f32x4*)(b_mod + D + c);
; #pragma unroll
;                 for (int p = 0; p < 8; ++p) { sh += *(const f32x4*)(part + (p * 3 + ms) * (NMOD * D) + c); sc += *(const f32x4*)(part + (p * 3 + ms) * (NMOD * D) + D + c); }
;                 shv[j] = sh; wv[j] = *(const f32x4*)(IN(6) + c) * (sc + 1.0f); }
;             if (ms < 2) norm_rows(x + (size_t)ms * L * D, xn + (size_t)ms * L * D, L, wv, shv, gw, ngw, lane);
;             else norm_rows(IN(2), xn + (size_t)T * D, TC, wv, shv, gw, ngw, lane);
.LBB0_227:
	s_mul_i32 s26, s4, 0x2200
	v_and_b32_e32 v6, 63, v176
	v_mul_u32_u24_e32 v6, 0x88, v6
	v_add_u32_e32 v6, s26, v6
	ds_read2_b64 v[52:55], v6 offset0:1 offset1:0
	ds_read2_b64 v[60:63], v6 offset0:3 offset1:2
	ds_read2_b64 v[68:71], v6 offset0:5 offset1:4
	ds_read2_b64 v[76:79], v6 offset0:7 offset1:6
	ds_read2_b64 v[56:59], v6 offset0:9 offset1:8
	ds_read2_b64 v[64:67], v6 offset0:11 offset1:10
	ds_read2_b64 v[72:75], v6 offset0:13 offset1:12
	ds_read2_b64 v[80:83], v6 offset0:15 offset1:14
	s_mov_b64 s[6:7], -1
	s_cmp_lg_u32 s4, 2
	s_waitcnt lgkmcnt(0)
	s_cbranch_scc0 .LBB0_231
	s_andn2_b64 vcc, exec, s[14:15]
	v_mov_b64_e32 v[84:85], v[48:49]
	v_mov_b64_e32 v[86:87], v[44:45]
	s_mov_b32 s5, s16
	s_cbranch_vccnz .LBB0_230
